# level-1 scan tasks start when their group's 16 prepared chunks are published (write-through stores + per-group counters) instead of waiting at barrier 4; mid-group pairs moved to the dead in-projectio
# speedup vs baseline: 1.0162x; 1.0026x over previous
.LBB0_313:
	v_or_b32_e32 v2, s50, v233
	v_mul_u32_u24_e32 v2, 0x110, v2
	v_add3_u32 v10, v168, v2, v235
	v_add_u32_e32 v2, s51, v10
	v_add_u32_e32 v6, 0x8800, v2
	s_waitcnt lgkmcnt(0)
	s_barrier
	ds_read2_b64 v[2:5], v6 offset0:128 offset1:130
	ds_read2_b64 v[6:9], v6 offset0:132 offset1:134
	v_lshl_add_u64 v[14:15], s[0:1], 0, v[178:179]
	s_andn2_b64 vcc, exec, s[42:43]
	s_waitcnt vmcnt(1)
	v_mov_b32_e32 v167, v139
	s_waitcnt lgkmcnt(1)
	global_store_dwordx4 v[14:15], v[2:5], off sc1
	s_waitcnt lgkmcnt(0)
	global_store_dwordx4 v[14:15], v[6:9], off offset:1024 sc1
	s_waitcnt vmcnt(2)
	v_mov_b32_e32 v166, v232
	v_add_u32_e32 v2, s96, v10
	v_add_u32_e32 v2, 0x8800, v2
	v_add_u32_e32 v10, s97, v10
	ds_read2_b64 v[2:5], v2 offset0:128 offset1:130
	v_add_u32_e32 v10, 0x8800, v10
	ds_read2_b64 v[10:13], v10 offset0:132 offset1:134
	v_lshl_add_u64 v[6:7], s[0:1], 0, v[180:181]
	s_waitcnt lgkmcnt(1)
	global_store_dwordx4 v[6:7], v[2:5], off sc1
	s_nop 1
	v_lshl_add_u64 v[2:3], s[0:1], 0, v[182:183]
	s_waitcnt lgkmcnt(0)
	global_store_dwordx4 v[2:3], v[10:13], off sc1
	s_barrier
	s_cbranch_vccz .LBB0_427

.LBB0_335:
	s_andn2_b64 vcc, exec, s[28:29]
	s_ashr_i32 s23, s22, 31
	s_cbranch_vccnz .LBB0_339
	v_and_b32_e32 v2, 64, v229
	v_add_u32_e32 v3, -1, v229
	v_cmp_lt_i32_e32 vcc, v3, v2
	v_add_u32_e32 v4, -2, v229
	v_add_u32_e32 v5, -4, v229
	v_cndmask_b32_e32 v3, v3, v229, vcc
	v_lshlrev_b32_e32 v3, 2, v3
	ds_bpermute_b32 v3, v3, v167
	v_cmp_lt_i32_e32 vcc, v4, v2
	v_readlane_b32 s0, v254, 29
	v_readlane_b32 s1, v254, 30
	v_cndmask_b32_e32 v4, v4, v229, vcc
	s_waitcnt lgkmcnt(0)
	v_add_f32_e32 v3, v167, v3
	v_cndmask_b32_e64 v3, v3, v167, s[4:5]
	v_lshlrev_b32_e32 v4, 2, v4
	ds_bpermute_b32 v4, v4, v3
	v_cmp_lt_i32_e32 vcc, v5, v2
	s_waitcnt lgkmcnt(0)
	v_add_f32_e32 v4, v3, v4
	v_cndmask_b32_e64 v3, v4, v3, s[0:1]
	v_cndmask_b32_e32 v4, v5, v229, vcc
	v_lshlrev_b32_e32 v4, 2, v4
	ds_bpermute_b32 v4, v4, v3
	v_add_u32_e32 v5, -8, v229
	v_cmp_lt_i32_e32 vcc, v5, v2
	v_readlane_b32 s0, v254, 27
	v_readlane_b32 s1, v254, 28
	s_waitcnt lgkmcnt(0)
	v_add_f32_e32 v4, v3, v4
	v_cndmask_b32_e64 v3, v4, v3, s[12:13]
	v_cndmask_b32_e32 v4, v5, v229, vcc
	v_lshlrev_b32_e32 v4, 2, v4
	ds_bpermute_b32 v4, v4, v3
	v_add_u32_e32 v5, -16, v229
	v_cmp_lt_i32_e32 vcc, v5, v2
	s_waitcnt lgkmcnt(0)
	v_add_f32_e32 v4, v3, v4
	v_cndmask_b32_e64 v3, v4, v3, s[14:15]
	v_cndmask_b32_e32 v4, v5, v229, vcc
	v_lshlrev_b32_e32 v4, 2, v4
	ds_bpermute_b32 v4, v4, v3
	v_subrev_u32_e32 v5, 32, v229
	v_cmp_lt_i32_e32 vcc, v5, v2
	s_waitcnt lgkmcnt(0)
	v_add_f32_e32 v4, v3, v4
	v_cndmask_b32_e32 v2, v5, v229, vcc
	v_cndmask_b32_e64 v3, v4, v3, s[16:17]
	v_lshlrev_b32_e32 v2, 2, v2
	ds_bpermute_b32 v2, v2, v3
	s_waitcnt lgkmcnt(0)
	v_add_f32_e32 v2, v3, v2
	v_cndmask_b32_e64 v3, v2, v3, s[0:1]
	ds_bpermute_b32 v2, v230, v3
	v_mul_f32_e32 v4, 0x3fb8aa3b, v3
	v_exp_f32_e32 v4, v4
	s_waitcnt lgkmcnt(0)
	v_sub_f32_e32 v5, v2, v3
	v_mul_f32_e32 v5, 0x3fb8aa3b, v5
	v_exp_f32_e32 v5, v5
	ds_write2st64_b32 v186, v166, v3 offset1:1
	ds_write2st64_b32 v186, v4, v5 offset0:2 offset1:3
	s_and_saveexec_b64 s[0:1], s[4:5]
	s_cbranch_execz .LBB0_338
	v_mul_f32_e32 v2, 0x3fb8aa3b, v2
	v_exp_f32_e32 v2, v2
	s_lshl_b64 s[18:19], s[22:23], 2
	v_readlane_b32 s21, v254, 31
	s_add_u32 s18, s21, s18
	v_readlane_b32 s21, v254, 33
	s_addc_u32 s19, s21, s19
	global_store_dword v138, v2, s[18:19] sc1

.LBB0_343:
	s_nop 2
	v_lshl_add_u64 v[2:3], s[0:1], 0, v[174:175]
	s_mov_b32 s21, s20
	v_add_co_u32_e32 v2, vcc, 0x10000, v2
	s_mov_b32 s22, s20
	s_mov_b32 s23, s20
	v_mov_b64_e32 v[4:5], s[20:21]
	v_addc_co_u32_e32 v3, vcc, 0, v3, vcc
	v_mov_b64_e32 v[6:7], s[22:23]
	global_store_dwordx4 v[2:3], v[4:7], off offset:2048 sc1
	global_store_dwordx4 v[2:3], v[4:7], off offset:3072 sc1

.LBB0_346:
	s_add_u32 s18, s0, s18
	v_cvt_pk_bf16_f32 v5, v6, v7
	v_lshl_add_u32 v6, v11, 10, v8
	s_addc_u32 s19, s1, s19
	v_ashrrev_i32_e32 v7, 31, v6
	s_add_i32 s86, s86, 3
	s_add_i32 s85, s85, 24
	s_add_i32 s45, s45, 48
	s_add_i32 s44, s44, 12
	s_addk_i32 s21, 0x60
	v_lshl_add_u64 v[6:7], s[18:19], 0, v[6:7]
	s_cmp_lt_i32 s87, 29
	v_add_u32_e32 v10, 3, v10
	global_store_dwordx4 v[6:7], v[2:5], off sc1
	s_cbranch_scc0 .LBB0_354

.LBB0_352:
	ds_read2_b32 v[22:23], v20 offset0:64 offset1:65
	ds_read2_b32 v[24:25], v20 offset0:66 offset1:67
	ds_read2_b32 v[30:31], v20 offset0:72 offset1:73
	ds_read2_b32 v[32:33], v20 offset0:74 offset1:75
	v_cmp_lt_i32_e32 vcc, -1, v18
	s_waitcnt lgkmcnt(3)
	v_sub_f32_e32 v21, v19, v22
	v_sub_f32_e32 v23, v19, v23
	v_mul_f32_e32 v21, 0x3fb8aa3b, v21
	v_exp_f32_e32 v22, v21
	v_mul_f32_e32 v21, 0x3fb8aa3b, v23
	v_exp_f32_e32 v23, v21
	s_waitcnt lgkmcnt(2)
	v_sub_f32_e32 v21, v19, v24
	v_mul_f32_e32 v21, 0x3fb8aa3b, v21
	v_pk_mul_f32 v[2:3], v[2:3], v[22:23]
	v_exp_f32_e32 v22, v21
	v_sub_f32_e32 v21, v19, v25
	v_mul_f32_e32 v21, 0x3fb8aa3b, v21
	v_exp_f32_e32 v23, v21
	s_waitcnt lgkmcnt(1)
	v_sub_f32_e32 v21, v19, v30
	v_mul_f32_e32 v21, 0x3fb8aa3b, v21
	v_exp_f32_e32 v24, v21
	v_sub_f32_e32 v21, v19, v31
	v_mul_f32_e32 v21, 0x3fb8aa3b, v21
	v_exp_f32_e32 v25, v21
	s_waitcnt lgkmcnt(0)
	v_sub_f32_e32 v21, v19, v32
	v_cvt_pk_bf16_f32 v2, v2, v3
	v_mul_f32_e32 v21, 0x3fb8aa3b, v21
	v_cndmask_b32_e32 v3, 0, v2, vcc
	v_lshrrev_b32_e32 v2, 16, v2
	v_cmp_lt_i32_e32 vcc, 0, v18
	v_exp_f32_e32 v30, v21
	v_sub_f32_e32 v21, v19, v33
	v_pk_mul_f32 v[4:5], v[4:5], v[22:23]
	v_cndmask_b32_e32 v2, 0, v2, vcc
	v_mul_f32_e32 v21, 0x3fb8aa3b, v21
	ds_read2_b32 v[22:23], v20 offset0:80 offset1:81
	v_perm_b32 v2, v2, v3, s84
	v_cvt_pk_bf16_f32 v3, v4, v5
	v_cmp_lt_i32_e32 vcc, 1, v18
	v_exp_f32_e32 v31, v21
	v_pk_mul_f32 v[6:7], v[6:7], v[24:25]
	v_cndmask_b32_e32 v4, 0, v3, vcc
	v_lshrrev_b32_e32 v3, 16, v3
	v_cmp_lt_i32_e32 vcc, 2, v18
	v_pk_mul_f32 v[8:9], v[8:9], v[30:31]
	ds_read2_b32 v[24:25], v20 offset0:82 offset1:83
	ds_read2_b32 v[30:31], v20 offset0:88 offset1:89
	ds_read2_b32 v[20:21], v20 offset0:90 offset1:91
	v_cndmask_b32_e32 v3, 0, v3, vcc
	v_perm_b32 v3, v3, v4, s84
	v_cvt_pk_bf16_f32 v4, v6, v7
	v_cmp_lt_i32_e32 vcc, 7, v18
	s_waitcnt lgkmcnt(3)
	v_sub_f32_e32 v22, v19, v22
	v_sub_f32_e32 v23, v19, v23
	v_cndmask_b32_e32 v5, 0, v4, vcc
	v_lshrrev_b32_e32 v4, 16, v4
	v_cmp_lt_i32_e32 vcc, 8, v18
	v_mul_f32_e32 v22, 0x3fb8aa3b, v22
	v_mul_f32_e32 v23, 0x3fb8aa3b, v23
	v_cndmask_b32_e32 v4, 0, v4, vcc
	v_perm_b32 v4, v4, v5, s84
	v_cvt_pk_bf16_f32 v5, v8, v9
	v_cmp_lt_i32_e32 vcc, 9, v18
	v_exp_f32_e32 v22, v22
	v_exp_f32_e32 v23, v23
	v_cndmask_b32_e32 v6, 0, v5, vcc
	v_lshrrev_b32_e32 v5, 16, v5
	v_cmp_lt_i32_e32 vcc, 10, v18
	s_waitcnt lgkmcnt(2)
	v_sub_f32_e32 v24, v19, v24
	v_sub_f32_e32 v25, v19, v25
	v_cndmask_b32_e32 v5, 0, v5, vcc
	v_mul_f32_e32 v24, 0x3fb8aa3b, v24
	v_mul_f32_e32 v25, 0x3fb8aa3b, v25
	s_waitcnt lgkmcnt(1)
	v_sub_f32_e32 v29, v19, v30
	v_perm_b32 v5, v5, v6, s84
	v_lshl_add_u32 v6, v231, 4, v194
	v_exp_f32_e32 v24, v24
	v_exp_f32_e32 v25, v25
	v_mul_f32_e32 v29, 0x3fb8aa3b, v29
	v_ashrrev_i32_e32 v7, 31, v6
	v_exp_f32_e32 v30, v29
	v_sub_f32_e32 v29, v19, v31
	v_pk_mul_f32 v[10:11], v[10:11], v[22:23]
	v_lshl_add_u64 v[8:9], s[18:19], 0, v[6:7]
	v_mul_f32_e32 v29, 0x3fb8aa3b, v29
	global_store_dwordx4 v[8:9], v[2:5], off sc1
	v_cmp_lt_i32_e32 vcc, 15, v18
	v_exp_f32_e32 v31, v29
	v_cvt_pk_bf16_f32 v2, v10, v11
	v_cndmask_b32_e32 v3, 0, v2, vcc
	v_cmp_lt_i32_e32 vcc, 16, v18
	s_waitcnt lgkmcnt(0)
	v_sub_f32_e32 v20, v19, v20
	v_sub_f32_e32 v19, v19, v21
	v_pk_mul_f32 v[12:13], v[12:13], v[24:25]
	v_cndmask_b32_sdwa v2, v138, v2, vcc dst_sel:DWORD dst_unused:UNUSED_PAD src0_sel:DWORD src1_sel:WORD_1
	v_mul_f32_e32 v20, 0x3fb8aa3b, v20
	v_mul_f32_e32 v19, 0x3fb8aa3b, v19
	v_perm_b32 v2, v2, v3, s84
	v_cvt_pk_bf16_f32 v3, v12, v13
	v_cmp_lt_i32_e32 vcc, 17, v18
	v_exp_f32_e32 v20, v20
	v_exp_f32_e32 v21, v19
	v_cndmask_b32_e32 v4, 0, v3, vcc
	v_cmp_lt_i32_e32 vcc, 18, v18
	v_pk_mul_f32 v[14:15], v[14:15], v[30:31]
	v_pk_mul_f32 v[16:17], v[16:17], v[20:21]
	v_cndmask_b32_sdwa v3, v138, v3, vcc dst_sel:DWORD dst_unused:UNUSED_PAD src0_sel:DWORD src1_sel:WORD_1
	v_perm_b32 v3, v3, v4, s84
	v_cvt_pk_bf16_f32 v4, v14, v15
	v_cmp_lt_i32_e32 vcc, 23, v18
	v_add_u32_e32 v6, 0x400, v6
	s_nop 0
	v_cndmask_b32_e32 v5, 0, v4, vcc
	v_cmp_lt_i32_e32 vcc, 24, v18
	s_nop 1
	v_cndmask_b32_sdwa v4, v138, v4, vcc dst_sel:DWORD dst_unused:UNUSED_PAD src0_sel:DWORD src1_sel:WORD_1
	v_perm_b32 v4, v4, v5, s84
	v_cvt_pk_bf16_f32 v5, v16, v17
	v_cmp_lt_i32_e32 vcc, 25, v18
	s_nop 1
	v_cndmask_b32_e32 v7, 0, v5, vcc
	v_cmp_lt_i32_e32 vcc, 26, v18
	s_nop 1
	v_cndmask_b32_sdwa v5, v138, v5, vcc dst_sel:DWORD dst_unused:UNUSED_PAD src0_sel:DWORD src1_sel:WORD_1
	v_perm_b32 v5, v5, v7, s84
	v_ashrrev_i32_e32 v7, 31, v6
	v_lshl_add_u64 v[6:7], s[18:19], 0, v[6:7]
	global_store_dwordx4 v[6:7], v[2:5], off sc1
	s_andn2_b64 vcc, exec, s[40:41]
	s_cbranch_vccnz .LBB0_342
.LBB0_353:
	s_nop 4
	v_or_b32_e32 v2, s52, v233
	v_mad_u32_u24 v50, v2, s47, v27
	ds_read_b128 v[2:5], v50 offset:18432
	v_or_b32_e32 v29, 32, v233
	v_mul_u32_u24_e32 v6, 0x110, v29
	v_add3_u32 v70, v168, v6, v26
	ds_read_b128 v[6:9], v70 offset:1024
	s_waitcnt lgkmcnt(2)
	ds_read_b128 v[18:21], v50 offset:18464
	ds_read_b128 v[22:25], v70 offset:1056
	v_add_u32_e32 v30, s52, v28
	v_lshl_add_u32 v31, v233, 2, v168
	ds_read_b32 v72, v31 offset:384
	v_sub_u32_e32 v29, v29, v30
	s_waitcnt lgkmcnt(3)
	v_mfma_f32_32x32x16_bf16 v[2:17], v[2:5], v[6:9], 0
	ds_read_b128 v[30:33], v50 offset:18496
	v_lshl_add_u32 v71, s52, 2, v27
	v_cmp_lt_i32_e32 vcc, -1, v29
	s_waitcnt lgkmcnt(2)
	v_mfma_f32_32x32x16_bf16 v[2:17], v[18:21], v[22:25], v[2:17]
	ds_read2_b32 v[62:63], v71 offset0:64 offset1:65
	ds_read2_b32 v[64:65], v71 offset0:66 offset1:67
	ds_read2_b32 v[66:67], v71 offset0:72 offset1:73
	ds_read2_b32 v[68:69], v71 offset0:74 offset1:75
	ds_read_b128 v[18:21], v70 offset:1088
	ds_read_b128 v[34:37], v50 offset:18528
	ds_read_b128 v[38:41], v50 offset:18560
	ds_read_b128 v[42:45], v50 offset:18592
	ds_read_b128 v[46:49], v70 offset:1120
	s_waitcnt lgkmcnt(8)
	v_sub_f32_e32 v62, v72, v62
	v_sub_f32_e32 v63, v72, v63
	s_waitcnt lgkmcnt(4)
	v_mfma_f32_32x32x16_bf16 v[2:17], v[30:33], v[18:21], v[2:17]
	ds_read_b128 v[30:33], v50 offset:18624
	ds_read_b128 v[18:21], v50 offset:18656
	ds_read_b128 v[50:53], v70 offset:1152
	ds_read_b128 v[54:57], v70 offset:1184
	ds_read_b128 v[58:61], v70 offset:1216
	ds_read_b128 v[22:25], v70 offset:1248
	s_waitcnt lgkmcnt(6)
	v_mfma_f32_32x32x16_bf16 v[2:17], v[34:37], v[46:49], v[2:17]
	v_sub_f32_e32 v34, v72, v64
	v_sub_f32_e32 v35, v72, v65
	v_mul_f32_e32 v48, 0x3fb8aa3b, v62
	v_sub_f32_e32 v36, v72, v66
	v_sub_f32_e32 v37, v72, v67
	v_mul_f32_e32 v49, 0x3fb8aa3b, v37
	v_sub_f32_e32 v46, v72, v68
	s_waitcnt lgkmcnt(3)
	v_mfma_f32_32x32x16_bf16 v[2:17], v[38:41], v[50:53], v[2:17]
	v_mul_f32_e32 v38, 0x3fb8aa3b, v63
	v_mul_f32_e32 v39, 0x3fb8aa3b, v34
	v_mul_f32_e32 v40, 0x3fb8aa3b, v35
	v_exp_f32_e32 v34, v48
	v_exp_f32_e32 v35, v38
	v_mul_f32_e32 v41, 0x3fb8aa3b, v36
	v_exp_f32_e32 v36, v39
	s_waitcnt lgkmcnt(2)
	v_mfma_f32_32x32x16_bf16 v[2:17], v[42:45], v[54:57], v[2:17]
	v_exp_f32_e32 v37, v40
	v_exp_f32_e32 v38, v41
	v_exp_f32_e32 v39, v49
	v_sub_f32_e32 v47, v72, v69
	v_mul_f32_e32 v46, 0x3fb8aa3b, v46
	v_mul_f32_e32 v47, 0x3fb8aa3b, v47
	v_exp_f32_e32 v40, v46
	s_waitcnt lgkmcnt(1)
	v_mfma_f32_32x32x16_bf16 v[2:17], v[30:33], v[58:61], v[2:17]
	ds_read2_b32 v[30:31], v71 offset0:80 offset1:81
	v_exp_f32_e32 v41, v47
	ds_read2_b32 v[32:33], v71 offset0:82 offset1:83
	ds_read2_b32 v[42:43], v71 offset0:88 offset1:89
	ds_read2_b32 v[44:45], v71 offset0:90 offset1:91
	s_waitcnt lgkmcnt(3)
	v_sub_f32_e32 v30, v72, v30
	v_sub_f32_e32 v31, v72, v31
	v_mfma_f32_32x32x16_bf16 v[2:17], v[18:21], v[22:25], v[2:17]
	v_mul_f32_e32 v30, 0x3fb8aa3b, v30
	v_mul_f32_e32 v31, 0x3fb8aa3b, v31
	v_exp_f32_e32 v30, v30
	v_exp_f32_e32 v31, v31
	s_waitcnt lgkmcnt(2)
	v_sub_f32_e32 v18, v72, v32
	v_sub_f32_e32 v19, v72, v33
	v_mul_f32_e32 v18, 0x3fb8aa3b, v18
	s_nop 3
	v_pk_mul_f32 v[2:3], v[2:3], v[34:35]
	v_pk_mul_f32 v[4:5], v[4:5], v[36:37]
	v_cvt_pk_bf16_f32 v2, v2, v3
	v_cndmask_b32_e32 v3, 0, v2, vcc
	v_lshrrev_b32_e32 v2, 16, v2
	v_cmp_lt_i32_e32 vcc, 0, v29
	v_pk_mul_f32 v[6:7], v[6:7], v[38:39]
	v_pk_mul_f32 v[8:9], v[8:9], v[40:41]
	v_cndmask_b32_e32 v2, 0, v2, vcc
	v_perm_b32 v2, v2, v3, s84
	v_cvt_pk_bf16_f32 v3, v4, v5
	v_cmp_lt_i32_e32 vcc, 1, v29
	v_mul_f32_e32 v19, 0x3fb8aa3b, v19
	v_exp_f32_e32 v18, v18
	v_cndmask_b32_e32 v4, 0, v3, vcc
	v_lshrrev_b32_e32 v3, 16, v3
	v_cmp_lt_i32_e32 vcc, 2, v29
	v_exp_f32_e32 v19, v19
	s_waitcnt lgkmcnt(1)
	v_sub_f32_e32 v20, v72, v42
	v_cndmask_b32_e32 v3, 0, v3, vcc
	v_perm_b32 v3, v3, v4, s84
	v_cvt_pk_bf16_f32 v4, v6, v7
	v_cmp_lt_i32_e32 vcc, 7, v29
	v_sub_f32_e32 v21, v72, v43
	v_pk_mul_f32 v[10:11], v[10:11], v[30:31]
	v_cndmask_b32_e32 v5, 0, v4, vcc
	v_lshrrev_b32_e32 v4, 16, v4
	v_cmp_lt_i32_e32 vcc, 8, v29
	v_mul_f32_e32 v20, 0x3fb8aa3b, v20
	v_mul_f32_e32 v21, 0x3fb8aa3b, v21
	v_cndmask_b32_e32 v4, 0, v4, vcc
	v_perm_b32 v4, v4, v5, s84
	v_cvt_pk_bf16_f32 v5, v8, v9
	v_cmp_lt_i32_e32 vcc, 9, v29
	v_exp_f32_e32 v20, v20
	v_exp_f32_e32 v21, v21
	v_cndmask_b32_e32 v6, 0, v5, vcc
	v_lshrrev_b32_e32 v5, 16, v5
	v_cmp_lt_i32_e32 vcc, 10, v29
	s_waitcnt lgkmcnt(0)
	v_sub_f32_e32 v22, v72, v44
	v_sub_f32_e32 v23, v72, v45
	v_cndmask_b32_e32 v5, 0, v5, vcc
	v_perm_b32 v5, v5, v6, s84
	v_lshl_add_u32 v6, v231, 4, s53
	v_ashrrev_i32_e32 v7, 31, v6
	v_lshl_add_u64 v[8:9], s[18:19], 0, v[6:7]
	global_store_dwordx4 v[8:9], v[2:5], off sc1
	v_cmp_lt_i32_e32 vcc, 15, v29
	v_pk_mul_f32 v[12:13], v[12:13], v[18:19]
	v_cvt_pk_bf16_f32 v2, v10, v11
	v_cndmask_b32_e32 v3, 0, v2, vcc
	v_cmp_lt_i32_e32 vcc, 16, v29
	v_mul_f32_e32 v22, 0x3fb8aa3b, v22
	v_mul_f32_e32 v23, 0x3fb8aa3b, v23
	v_cndmask_b32_sdwa v2, v138, v2, vcc dst_sel:DWORD dst_unused:UNUSED_PAD src0_sel:DWORD src1_sel:WORD_1
	v_perm_b32 v2, v2, v3, s84
	v_cvt_pk_bf16_f32 v3, v12, v13
	v_cmp_lt_i32_e32 vcc, 17, v29
	v_exp_f32_e32 v22, v22
	v_exp_f32_e32 v23, v23
	v_cndmask_b32_e32 v4, 0, v3, vcc
	v_cmp_lt_i32_e32 vcc, 18, v29
	v_pk_mul_f32 v[14:15], v[14:15], v[20:21]
	v_pk_mul_f32 v[16:17], v[16:17], v[22:23]
	v_cndmask_b32_sdwa v3, v138, v3, vcc dst_sel:DWORD dst_unused:UNUSED_PAD src0_sel:DWORD src1_sel:WORD_1
	v_perm_b32 v3, v3, v4, s84
	v_cvt_pk_bf16_f32 v4, v14, v15
	v_cmp_lt_i32_e32 vcc, 23, v29
	v_add_u32_e32 v6, 0x400, v6
	s_nop 0
	v_cndmask_b32_e32 v5, 0, v4, vcc
	v_cmp_lt_i32_e32 vcc, 24, v29
	s_nop 1
	v_cndmask_b32_sdwa v4, v138, v4, vcc dst_sel:DWORD dst_unused:UNUSED_PAD src0_sel:DWORD src1_sel:WORD_1
	v_perm_b32 v4, v4, v5, s84
	v_cvt_pk_bf16_f32 v5, v16, v17
	v_cmp_lt_i32_e32 vcc, 25, v29
	s_nop 1
	v_cndmask_b32_e32 v7, 0, v5, vcc
	v_cmp_lt_i32_e32 vcc, 26, v29
	s_nop 1
	v_cndmask_b32_sdwa v5, v138, v5, vcc dst_sel:DWORD dst_unused:UNUSED_PAD src0_sel:DWORD src1_sel:WORD_1
	v_perm_b32 v5, v5, v7, s84
	v_ashrrev_i32_e32 v7, 31, v6
	v_lshl_add_u64 v[6:7], s[18:19], 0, v[6:7]
	global_store_dwordx4 v[6:7], v[2:5], off sc1
	s_and_b64 vcc, exec, s[2:3]
	s_cbranch_vccnz .LBB0_343
	s_branch .LBB0_344

.LBB0_421:
	v_mad_u32_u24 v65, v233, s47, v171
	v_add_u32_e32 v30, v65, v26
	v_add_u32_e32 v31, s48, v30
	s_waitcnt lgkmcnt(0)
	s_barrier
	ds_read_b128 v[50:53], v31
	v_lshlrev_b32_e32 v235, 3, v234
	v_lshrrev_b32_e32 v2, 2, v231
	v_and_or_b32 v2, v2, 3, v235
	v_mad_u64_u32 v[62:63], s[18:19], v2, s47, v[176:177]
	v_lshlrev_b32_e32 v2, 2, v231
	v_and_b32_e32 v63, 16, v231
	v_and_b32_e32 v64, 12, v2
	v_or3_b32 v2, s55, v63, v64
	v_lshl_add_u32 v32, v2, 1, v62
	ds_read_b64_tr_b16 v[2:3], v32
	ds_read_b64_tr_b16 v[4:5], v32 offset:1088
	ds_read_b128 v[66:69], v31 offset:32
	ds_read_b64_tr_b16 v[18:19], v32 offset:4352
	ds_read_b64_tr_b16 v[20:21], v32 offset:5440
	s_waitcnt lgkmcnt(3)
	v_mfma_f32_32x32x16_bf16 v[2:17], v[50:53], v[2:5], 0
	ds_read_b128 v[22:25], v30 offset:8704
	ds_read_b128 v[26:29], v30 offset:8736
	v_add_u32_e32 v65, v65, v235
	s_add_u32 s18, s0, 0x8000
	s_addc_u32 s19, s1, 0
	s_waitcnt lgkmcnt(1)
	v_cvt_pk_bf16_f32 v70, v22, v23
	v_cvt_pk_bf16_f32 v71, v24, v25
	s_waitcnt lgkmcnt(0)
	v_cvt_pk_bf16_f32 v72, v26, v27
	v_mfma_f32_32x32x16_bf16 v[2:17], v[66:69], v[18:21], v[2:17]
	ds_read_b128 v[18:21], v30 offset:8768
	ds_read_b128 v[22:25], v30 offset:8800
	v_cvt_pk_bf16_f32 v73, v28, v29
	s_and_b64 vcc, s[36:37], exec
	s_waitcnt lgkmcnt(1)
	v_cvt_pk_bf16_f32 v140, v18, v19
	v_cvt_pk_bf16_f32 v141, v20, v21
	s_nop 4
	v_cvt_pk_bf16_f32 v54, v2, v3
	v_cvt_pk_bf16_f32 v55, v4, v5
	v_cvt_pk_bf16_f32 v56, v6, v7
	v_cvt_pk_bf16_f32 v57, v8, v9
	ds_read_b128 v[144:147], v31 offset:8832
	ds_read_b64_tr_b16 v[18:19], v32 offset:8704
	ds_read_b64_tr_b16 v[20:21], v32 offset:9792
	ds_read_b128 v[152:155], v31 offset:8864
	ds_read_b64_tr_b16 v[74:75], v32 offset:13056
	ds_read_b64_tr_b16 v[76:77], v32 offset:14144
	v_mfma_f32_32x32x16_bf16 v[34:49], v[70:73], v[54:57], 0
	s_waitcnt lgkmcnt(6)
	v_cvt_pk_bf16_f32 v142, v22, v23
	v_cvt_pk_bf16_f32 v143, v24, v25
	v_cvt_pk_bf16_f32 v58, v10, v11
	v_cvt_pk_bf16_f32 v59, v12, v13
	v_cvt_pk_bf16_f32 v60, v14, v15
	v_cvt_pk_bf16_f32 v61, v16, v17
	ds_read2_b64 v[148:151], v65 offset0:16 offset1:18
	s_waitcnt lgkmcnt(4)
	v_mfma_f32_32x32x16_bf16 v[18:33], v[144:147], v[18:21], 0
	ds_read2_b64 v[156:159], v65 offset0:20 offset1:22
	v_mfma_f32_32x32x16_bf16 v[34:49], v[140:143], v[58:61], v[34:49]
	s_waitcnt lgkmcnt(2)
	v_mfma_f32_32x32x16_bf16 v[18:33], v[152:155], v[74:77], v[18:33]
	s_nop 9
	v_cvt_pk_bf16_f32 v34, v34, v35
	v_cvt_pk_bf16_f32 v35, v36, v37
	v_cvt_pk_bf16_f32 v36, v38, v39
	v_cvt_pk_bf16_f32 v37, v40, v41
	s_waitcnt lgkmcnt(1)
	s_nop 0
	v_mfma_f32_32x32x16_bf16 v[18:33], v[148:151], v[34:37], v[18:33]
	v_cvt_pk_bf16_f32 v34, v42, v43
	v_cvt_pk_bf16_f32 v35, v44, v45
	v_cvt_pk_bf16_f32 v36, v46, v47
	v_cvt_pk_bf16_f32 v37, v48, v49
	s_waitcnt lgkmcnt(0)
	s_nop 0
	v_mfma_f32_32x32x16_bf16 v[18:33], v[156:159], v[34:37], v[18:33]
	s_cbranch_vccz .LBB0_423
	v_lshl_add_u32 v34, v231, 5, s93
	v_ashrrev_i32_e32 v35, 31, v34
	v_lshl_add_u64 v[36:37], s[18:19], 0, v[34:35]
	v_add_u32_e32 v34, 0x800, v34
	v_ashrrev_i32_e32 v35, 31, v34
	global_store_dwordx4 v[36:37], v[54:57], off sc1
	global_store_dwordx4 v[36:37], v[58:61], off offset:16 sc1
	v_lshl_add_u64 v[42:43], s[18:19], 0, v[34:35]
	s_nop 2
	v_cvt_pk_bf16_f32 v34, v18, v19
	v_cvt_pk_bf16_f32 v35, v20, v21
	v_cvt_pk_bf16_f32 v36, v22, v23
	v_cvt_pk_bf16_f32 v37, v24, v25
	v_cvt_pk_bf16_f32 v38, v26, v27
	v_cvt_pk_bf16_f32 v39, v28, v29
	v_cvt_pk_bf16_f32 v40, v30, v31
	v_cvt_pk_bf16_f32 v41, v32, v33
	global_store_dwordx4 v[42:43], v[34:37], off sc1
	global_store_dwordx4 v[42:43], v[38:41], off offset:16 sc1
.LBB0_423:
	s_nop 0
	v_or3_b32 v34, s94, v63, v64
	v_lshl_add_u32 v42, v34, 1, v62
	ds_read_b64_tr_b16 v[34:35], v42
	ds_read_b64_tr_b16 v[36:37], v42 offset:1088
	ds_read_b64_tr_b16 v[38:39], v42 offset:4352
	ds_read_b64_tr_b16 v[40:41], v42 offset:5440
	s_andn2_b64 vcc, exec, s[36:37]
	s_waitcnt lgkmcnt(2)
	v_mfma_f32_32x32x16_bf16 v[50:65], v[50:53], v[34:37], 0
	s_waitcnt lgkmcnt(0)
	v_mfma_f32_32x32x16_bf16 v[50:65], v[66:69], v[38:41], v[50:65]
	s_nop 11
	v_cvt_pk_bf16_f32 v160, v50, v51
	v_cvt_pk_bf16_f32 v161, v52, v53
	v_cvt_pk_bf16_f32 v162, v54, v55
	v_cvt_pk_bf16_f32 v163, v56, v57
	v_cvt_pk_bf16_f32 v164, v58, v59
	v_cvt_pk_bf16_f32 v165, v60, v61
	v_mfma_f32_32x32x16_bf16 v[66:81], v[70:73], v[160:163], 0
	v_cvt_pk_bf16_f32 v166, v62, v63
	v_cvt_pk_bf16_f32 v167, v64, v65
	s_nop 1
	v_mfma_f32_32x32x16_bf16 v[66:81], v[140:143], v[164:167], v[66:81]
	ds_read_b64_tr_b16 v[34:35], v42 offset:8704
	ds_read_b64_tr_b16 v[36:37], v42 offset:9792
	ds_read_b64_tr_b16 v[140:141], v42 offset:13056
	ds_read_b64_tr_b16 v[142:143], v42 offset:14144
	s_waitcnt lgkmcnt(2)
	v_mfma_f32_32x32x16_bf16 v[34:49], v[144:147], v[34:37], 0
	s_nop 5
	v_cvt_pk_bf16_f32 v66, v66, v67
	v_cvt_pk_bf16_f32 v67, v68, v69
	v_cvt_pk_bf16_f32 v68, v70, v71
	v_cvt_pk_bf16_f32 v69, v72, v73
	s_waitcnt lgkmcnt(0)
	v_mfma_f32_32x32x16_bf16 v[34:49], v[152:155], v[140:143], v[34:49]
	v_mfma_f32_32x32x16_bf16 v[34:49], v[148:151], v[66:69], v[34:49]
	v_cvt_pk_bf16_f32 v66, v74, v75
	v_cvt_pk_bf16_f32 v67, v76, v77
	v_cvt_pk_bf16_f32 v68, v78, v79
	v_cvt_pk_bf16_f32 v69, v80, v81
	s_nop 1
	v_mfma_f32_32x32x16_bf16 v[34:49], v[156:159], v[66:69], v[34:49]
	s_cbranch_vccnz .LBB0_425
	v_lshl_add_u32 v66, v231, 5, s95
	v_ashrrev_i32_e32 v67, 31, v66
	v_lshl_add_u64 v[68:69], s[18:19], 0, v[66:67]
	v_add_u32_e32 v66, 0x800, v66
	v_ashrrev_i32_e32 v67, 31, v66
	global_store_dwordx4 v[68:69], v[160:163], off sc1
	global_store_dwordx4 v[68:69], v[164:167], off offset:16 sc1
	v_lshl_add_u64 v[74:75], s[18:19], 0, v[66:67]
	s_nop 2
	v_cvt_pk_bf16_f32 v66, v34, v35
	v_cvt_pk_bf16_f32 v67, v36, v37
	v_cvt_pk_bf16_f32 v68, v38, v39
	v_cvt_pk_bf16_f32 v69, v40, v41
	v_cvt_pk_bf16_f32 v70, v42, v43
	v_cvt_pk_bf16_f32 v71, v44, v45
	v_cvt_pk_bf16_f32 v72, v46, v47
	v_cvt_pk_bf16_f32 v73, v48, v49
	global_store_dwordx4 v[74:75], v[66:69], off sc1
	global_store_dwordx4 v[74:75], v[70:73], off offset:16 sc1

.LBB0_428:
	s_waitcnt vmcnt(0)
	s_barrier
	s_mov_b64 s[0:1], exec
	v_readlane_b32 s2, v254, 6
	v_readlane_b32 s3, v254, 7
	s_and_b64 s[2:3], s[0:1], s[2:3]
	s_mov_b64 exec, s[2:3]
	s_cbranch_execz .LBB0_480
	s_lshr_b32 s98, s64, 7
	s_lshl_b32 s98, s98, 4
	s_and_b32 s99, s64, 127
	s_lshr_b32 s99, s99, 3
	s_add_i32 s98, s98, s99
	s_lshl_b32 s98, s98, 8
	s_add_i32 s98, s98, 0xc000
	v_mov_b32_e32 v252, s98
	v_add_u32_e32 v251, 0x2000, v252
	v_mov_b32_e32 v253, 2
	global_atomic_add v252, v253, s[82:83]
	global_atomic_add v251, v253, s[82:83]
	s_add_i32 s2, 0, 0x26d60
	v_mov_b32_e32 v2, s2
	s_waitcnt vmcnt(0) expcnt(0) lgkmcnt(0)
	ds_read_b32 v4, v2
	s_add_i32 s2, 0, 0x26d64
	v_mov_b32_e32 v2, s2
	ds_read_b32 v2, v2
	s_waitcnt lgkmcnt(1)
	v_cmp_ne_u32_e32 vcc, 0, v4
	s_cbranch_vccnz .LBB0_444
	v_readlane_b32 s2, v254, 0
	v_readlane_b32 s3, v254, 1
	s_load_dwordx2 s[6:7], s[2:3], 0x4
	s_add_u32 s2, s82, 0x4200
	s_addc_u32 s3, s83, 0
	s_add_u32 s4, s82, 0x4400
	s_addc_u32 s5, s83, 0
	v_readlane_b32 s8, v254, 2
	s_waitcnt lgkmcnt(0)
	s_mul_i32 s33, s6, s8
	s_add_u32 s6, s82, 0x4500
	s_mul_i32 s33, s33, s7
	s_addc_u32 s7, s83, 0
	s_add_u32 s8, s82, 0x4600
	s_addc_u32 s9, s83, 0
	s_add_u32 s10, s82, 0x4700
	s_addc_u32 s11, s83, 0
	s_add_u32 s12, s82, 0x4800
	s_addc_u32 s13, s83, 0
	s_add_u32 s14, s82, 0x4900
	s_addc_u32 s15, s83, 0
	s_add_u32 s16, s82, 0x4a00
	s_addc_u32 s17, s83, 0
	s_add_u32 s18, s82, 0x4b00
	s_addc_u32 s19, s83, 0
	s_add_u32 s20, s82, 0x4c00
	s_addc_u32 s21, s83, 0
	s_add_u32 s22, s82, 0x4d00
	s_addc_u32 s23, s83, 0
	s_add_u32 s24, s82, 0x4e00
	s_addc_u32 s25, s83, 0
	s_add_u32 s26, s82, 0x4f00
	s_addc_u32 s27, s83, 0
	s_add_u32 s28, s82, 0x5000
	s_addc_u32 s29, s83, 0
	s_add_u32 s30, s82, 0x5100
	s_addc_u32 s31, s83, 0
	s_add_u32 s34, s82, 0x5200
	s_addc_u32 s35, s83, 0
	s_add_u32 s36, s82, 0x5300
	s_addc_u32 s37, s83, 0
	s_mov_b32 s44, 1
	v_mov_b32_e32 v18, 0
	s_branch .LBB0_432

.LBB0_446:
	s_or_b64 exec, exec, s[6:7]
	v_mov_b32_e32 v253, 0x7000
	global_load_dword v253, v253, s[82:83] offset:1280 sc1
	v_cvt_f32_u32_e32 v6, v4
	s_waitcnt vmcnt(0)
	v_readfirstlane_b32 s4, v5
	v_sub_u32_e32 v5, 0, v4
	v_rcp_iflag_f32_e32 v6, v6
	v_add_u32_e32 v7, s4, v3
	v_mul_f32_e32 v6, 0x4f7ffffe, v6
	v_cvt_u32_f32_e32 v6, v6
	v_mul_lo_u32 v3, v5, v6
	v_mul_hi_u32 v3, v6, v3
	v_add_u32_e32 v3, v6, v3
	v_mul_hi_u32 v3, v7, v3
	v_mul_lo_u32 v5, v3, v4
	v_sub_u32_e32 v5, v7, v5
	v_add_u32_e32 v6, 1, v3
	v_cmp_ge_u32_e32 vcc, v5, v4
	s_nop 1
	v_cndmask_b32_e32 v3, v3, v6, vcc
	v_sub_u32_e32 v6, v5, v4
	v_cndmask_b32_e32 v5, v5, v6, vcc
	v_add_u32_e32 v6, 1, v3
	v_cmp_ge_u32_e32 vcc, v5, v4
	v_add_u32_e32 v5, 1, v7
	s_nop 0
	v_cndmask_b32_e32 v3, v3, v6, vcc
	v_mul_lo_u32 v6, v4, v3
	v_add_u32_e32 v4, v6, v4
	v_cmp_ne_u32_e32 vcc, v5, v4
	s_and_saveexec_b64 s[4:5], vcc
	s_xor_b64 s[4:5], exec, s[4:5]
	s_cbranch_execz .LBB0_460
	s_waitcnt lgkmcnt(0)
	v_mov_b32_e32 v2, 0x7000
	buffer_inv sc1
.Lb3chk_spinN:
	v_readfirstlane_b32 s99, v253
	s_nop 3
	s_cmp_ge_u32 s99, 3
	s_cbranch_scc1 .Lsplit4_nl
	s_sleep 1
	v_mov_b32_e32 v253, 0x7000
	global_load_dword v253, v253, s[82:83] offset:1280 sc1
	s_waitcnt vmcnt(0)
	s_branch .Lb3chk_spinN

.LBB0_463:
	s_or_b64 exec, exec, s[6:7]
	v_cvt_f32_u32_e32 v5, v2
	s_waitcnt vmcnt(0)
	v_readfirstlane_b32 s4, v4
	s_add_u32 s6, s82, 0x7500
	s_addc_u32 s7, s83, 0
	v_rcp_iflag_f32_e32 v5, v5
	v_add_u32_e32 v3, s4, v3
	v_add_u32_e32 v6, 1, v3
	s_mov_b64 s[8:9], -1
	v_mul_f32_e32 v4, 0x4f7ffffe, v5
	v_cvt_u32_f32_e32 v4, v4
	v_sub_u32_e32 v5, 0, v2
	v_mul_lo_u32 v5, v5, v4
	v_mul_hi_u32 v5, v4, v5
	v_add_u32_e32 v4, v4, v5
	v_mul_hi_u32 v4, v3, v4
	v_mul_lo_u32 v5, v4, v2
	v_sub_u32_e32 v3, v3, v5
	v_add_u32_e32 v7, 1, v4
	v_cmp_ge_u32_e32 vcc, v3, v2
	v_sub_u32_e32 v5, v3, v2
	s_nop 0
	v_cndmask_b32_e32 v4, v4, v7, vcc
	v_cndmask_b32_e32 v3, v3, v5, vcc
	v_add_u32_e32 v5, 1, v4
	v_cmp_ge_u32_e32 vcc, v3, v2
	s_nop 1
	v_cndmask_b32_e32 v4, v4, v5, vcc
	v_mul_lo_u32 v3, v2, v4
	v_add_u32_e32 v2, v3, v2
	v_cmp_ne_u32_e32 vcc, v6, v2
	v_mov_b64_e32 v[2:3], s[6:7]
	s_and_saveexec_b64 s[4:5], vcc
	s_cbranch_execz .LBB0_475
	s_mov_b64 s[12:13], 0
.Lb3chk_spinL:
	v_readfirstlane_b32 s99, v253
	s_nop 3
	s_cmp_ge_u32 s99, 3
	s_cbranch_scc1 .Lsplit4_ld
	s_sleep 1
	v_mov_b32_e32 v253, 0x7000
	global_load_dword v253, v253, s[82:83] offset:1280 sc1
	s_waitcnt vmcnt(0)
	s_branch .Lb3chk_spinL

.LBB0_480:
	s_or_b64 exec, exec, s[0:1]
	v_mov_b32_e32 v184, v0
	s_waitcnt lgkmcnt(0)
	s_barrier
	s_mov_b32 s98, 0
	s_nop 0
	v_readfirstlane_b32 s54, v184
	s_ashr_i32 s0, s54, 6
	s_cmpk_gt_i32 s64, 0x7f
	v_writelane_b32 v254, s0, 27
	s_cselect_b64 s[0:1], -1, 0
	v_writelane_b32 v254, s0, 35
	v_and_b32_e32 v183, 63, v184
	s_and_b64 vcc, exec, s[0:1]
	v_writelane_b32 v254, s1, 36
	s_cbranch_vccz .LBB0_497
	s_cmpk_gt_u32 s64, 0x8f
	s_mov_b64 s[2:3], -1
	v_writelane_b32 v254, s54, 54
	s_cbranch_scc1 .LBB0_498
	s_mov_b64 s[4:5], 0
	s_andn2_b64 vcc, exec, s[2:3]
	s_mov_b64 s[0:1], 0
	s_cbranch_vccz .LBB0_580

.LBB0_652:
	s_mov_b64 s[100:101], exec
	v_readlane_b32 s99, v254, 6
	s_nop 3
	s_mov_b32 exec_lo, s99
	s_mov_b32 exec_hi, 0
	s_cbranch_execz .Ll1dep_join
	s_and_b32 s99, s64, 7
	s_lshl_b32 s99, s99, 3
	v_mov_b32_e32 v240, s99
	s_lshr_b32 s99, s64, 4
	v_add_u32_e32 v240, s99, v240
	v_lshlrev_b32_e32 v240, 8, v240
	v_add_u32_e32 v240, 0xc000, v240
	v_mov_b32_e32 v242, 0
.Ll1dep_spin:
	global_load_dword v241, v240, s[82:83] sc1
	s_waitcnt vmcnt(0)
	v_add_u32_e32 v242, 1, v242
	v_readfirstlane_b32 s99, v241
	s_nop 3
	s_cmp_ge_u32 s99, 16
	s_cbranch_scc1 .Ll1dep_join
	s_sleep 1
	v_readfirstlane_b32 s99, v242
	s_nop 3
	s_cmp_lt_u32 s99, 0x40001
	s_cbranch_scc1 .Ll1dep_spin
	v_mov_b32_e32 v241, 1
	v_mov_b32_e32 v242, 0x4000
	global_atomic_add v242, v241, s[82:83] offset:512
	s_waitcnt vmcnt(0)
.Ll1dep_join:
	s_mov_b64 exec, s[100:101]
	s_barrier
	v_writelane_b32 v254, s0, 37
	s_and_b32 s46, s64, 7
	v_cmp_gt_u32_e32 vcc, 16, v0
	v_writelane_b32 v254, s1, 38
	s_lshl_b32 s0, s46, 3
	s_ashr_i32 s1, s64, 4
	s_add_i32 s8, s0, s1
	s_lshr_b32 s0, s8, 28
	s_add_i32 s0, s8, s0
	s_ashr_i32 s47, s0, 4
	s_and_b32 s0, s0, -16
	s_sub_i32 s2, s8, s0
	v_writelane_b32 v254, s1, 39
	s_lshl_b32 s36, s47, 8
	s_lshl_b32 s38, s2, 4
	s_and_saveexec_b64 s[0:1], vcc
	s_cbranch_execz .LBB0_654
	s_ashr_i32 s37, s36, 31
	s_lshl_b64 s[4:5], s[36:37], 2
	s_add_u32 s3, s82, s4
	s_addc_u32 s6, s83, s5
	s_ashr_i32 s39, s38, 31
	s_lshl_b64 s[4:5], s[38:39], 2
	s_add_u32 s4, s3, s4
	v_lshlrev_b32_e32 v2, 2, v0
	s_addc_u32 s5, s6, s5
	v_mov_b32_e32 v3, 0
	v_lshl_add_u64 v[4:5], s[4:5], 0, v[2:3]
	v_add_co_u32_e32 v4, vcc, 0xb7e000, v4
	v_add_u32_e32 v2, 0, v2
	s_nop 0
	v_addc_co_u32_e32 v5, vcc, 0, v5, vcc
	global_load_dword v3, v[4:5], off
	v_add_u32_e32 v2, 0x24000, v2
	s_waitcnt vmcnt(0)
	ds_write_b32 v2, v3
	s_waitcnt lgkmcnt(0)
.LBB0_654:
	s_or_b64 exec, exec, s[0:1]
	s_ashr_i32 s70, s64, 3
	s_and_b32 s37, s70, 1
	s_cmp_eq_u32 s2, 15
	s_cselect_b64 s[0:1], -1, 0
	s_cmp_lg_u32 s2, 15
	s_cselect_b64 s[44:45], -1, 0
	s_and_b64 s[2:3], s[0:1], exec
	s_mov_b32 s2, s8
	s_cselect_b32 s39, 8, 16
	s_ashr_i32 s9, s8, 31
	v_writelane_b32 v254, s2, 40
	v_lshrrev_b32_e32 v186, 5, v183
	v_and_b32_e32 v185, 31, v184
	v_writelane_b32 v254, s3, 41
	s_lshl_b64 s[2:3], s[8:9], 16
	s_add_u32 s2, s82, s2
	s_addc_u32 s3, s83, s3
	s_add_u32 s4, s2, 0xf800000
	s_addc_u32 s5, s3, 0
	s_add_u32 s42, s2, 0x100000
	s_addc_u32 s43, s3, 0
	s_and_b64 s[2:3], s[0:1], exec
	s_mul_i32 s2, s39, 0x56
	s_cselect_b32 s35, s43, s5
	s_cselect_b32 s34, s42, s4
	s_lshr_b32 s2, s2, 8
	s_mul_i32 s2, s2, 3
	s_sub_i32 s2, s39, s2
	s_and_b32 s2, s2, 0xff
	s_mul_i32 s2, s2, 0xc000
	s_add_i32 s48, s2, 0
	v_readlane_b32 s4, v254, 27
	v_lshlrev_b32_e32 v178, 4, v183
	s_mov_b32 s33, 0
	s_mov_b64 s[2:3], -1
	s_cmp_lt_i32 s4, 4
	v_lshlrev_b32_e32 v187, 2, v186
	s_cbranch_scc0 .LBB0_667
	s_cmp_lg_u32 s37, 0
	s_cselect_b64 s[40:41], -1, 0
	s_cmp_lt_u32 s54, 64
	s_cselect_b64 s[2:3], -1, 0
	s_and_b64 s[50:51], s[40:41], s[2:3]
	v_cmp_eq_u32_e32 vcc, v187, v185
	s_and_b64 s[2:3], s[50:51], vcc
	v_or_b32_e32 v2, 1, v187
	v_cndmask_b32_e64 v66, 0, 1.0, s[2:3]
	v_cmp_eq_u32_e64 s[2:3], v2, v185
	s_and_b64 s[4:5], s[50:51], s[2:3]
	v_or_b32_e32 v2, 2, v187
	v_cndmask_b32_e64 v67, 0, 1.0, s[4:5]
	v_cmp_eq_u32_e64 s[4:5], v2, v185
	s_and_b64 s[6:7], s[50:51], s[4:5]
	v_or_b32_e32 v2, 3, v187
	v_cndmask_b32_e64 v68, 0, 1.0, s[6:7]
	v_cmp_eq_u32_e64 s[6:7], v2, v185
	s_and_b64 s[8:9], s[50:51], s[6:7]
	v_or_b32_e32 v2, 8, v187
	v_cndmask_b32_e64 v69, 0, 1.0, s[8:9]
	v_cmp_eq_u32_e64 s[8:9], v2, v185
	s_and_b64 s[10:11], s[50:51], s[8:9]
	v_or_b32_e32 v2, 9, v187
	v_cndmask_b32_e64 v70, 0, 1.0, s[10:11]
	v_cmp_eq_u32_e64 s[10:11], v2, v185
	s_and_b64 s[12:13], s[50:51], s[10:11]
	v_or_b32_e32 v2, 10, v187
	v_cndmask_b32_e64 v71, 0, 1.0, s[12:13]
	v_cmp_eq_u32_e64 s[12:13], v2, v185
	s_and_b64 s[14:15], s[50:51], s[12:13]
	v_or_b32_e32 v2, 11, v187
	v_cndmask_b32_e64 v72, 0, 1.0, s[14:15]
	v_cmp_eq_u32_e64 s[14:15], v2, v185
	s_and_b64 s[16:17], s[50:51], s[14:15]
	v_or_b32_e32 v2, 16, v187
	v_cndmask_b32_e64 v73, 0, 1.0, s[16:17]
	v_cmp_eq_u32_e64 s[16:17], v2, v185
	s_and_b64 s[18:19], s[50:51], s[16:17]
	v_or_b32_e32 v2, 17, v187
	v_cndmask_b32_e64 v74, 0, 1.0, s[18:19]
	v_cmp_eq_u32_e64 s[18:19], v2, v185
	s_and_b64 s[20:21], s[50:51], s[18:19]
	v_or_b32_e32 v2, 18, v187
	v_cndmask_b32_e64 v75, 0, 1.0, s[20:21]
	v_cmp_eq_u32_e64 s[20:21], v2, v185
	s_and_b64 s[22:23], s[50:51], s[20:21]
	v_or_b32_e32 v2, 19, v187
	v_cndmask_b32_e64 v76, 0, 1.0, s[22:23]
	v_cmp_eq_u32_e64 s[22:23], v2, v185
	s_and_b64 s[24:25], s[50:51], s[22:23]
	v_or_b32_e32 v2, 24, v187
	v_cndmask_b32_e64 v77, 0, 1.0, s[24:25]
	v_cmp_eq_u32_e64 s[24:25], v2, v185
	s_and_b64 s[26:27], s[50:51], s[24:25]
	v_or_b32_e32 v2, 25, v187
	v_cndmask_b32_e64 v78, 0, 1.0, s[26:27]
	v_cmp_eq_u32_e64 s[26:27], v2, v185
	s_and_b64 s[28:29], s[50:51], s[26:27]
	v_or_b32_e32 v2, 26, v187
	v_cndmask_b32_e64 v79, 0, 1.0, s[28:29]
	v_cmp_eq_u32_e64 s[28:29], v2, v185
	s_and_b64 s[30:31], s[50:51], s[28:29]
	v_or_b32_e32 v2, 27, v187
	v_cndmask_b32_e64 v80, 0, 1.0, s[30:31]
	v_cmp_eq_u32_e64 s[30:31], v2, v185
	s_and_b64 s[50:51], s[50:51], s[30:31]
	v_readlane_b32 s49, v254, 27
	s_cmp_eq_u32 s49, 1
	v_cndmask_b32_e64 v81, 0, 1.0, s[50:51]
	s_cselect_b64 s[50:51], -1, 0
	s_and_b64 s[50:51], s[40:41], s[50:51]
	s_and_b64 s[52:53], s[50:51], vcc
	s_waitcnt vmcnt(8)
	v_cndmask_b32_e64 v82, 0, 1.0, s[52:53]
	s_and_b64 s[52:53], s[50:51], s[2:3]
	v_cndmask_b32_e64 v83, 0, 1.0, s[52:53]
	s_and_b64 s[52:53], s[50:51], s[4:5]
	v_cndmask_b32_e64 v84, 0, 1.0, s[52:53]
	s_and_b64 s[52:53], s[50:51], s[6:7]
	v_cndmask_b32_e64 v85, 0, 1.0, s[52:53]
	s_and_b64 s[52:53], s[50:51], s[8:9]
	v_cndmask_b32_e64 v86, 0, 1.0, s[52:53]
	s_and_b64 s[52:53], s[50:51], s[10:11]
	v_cndmask_b32_e64 v87, 0, 1.0, s[52:53]
	s_and_b64 s[52:53], s[50:51], s[12:13]
	v_cndmask_b32_e64 v88, 0, 1.0, s[52:53]
	s_and_b64 s[52:53], s[50:51], s[14:15]
	v_cndmask_b32_e64 v89, 0, 1.0, s[52:53]
	s_and_b64 s[52:53], s[50:51], s[16:17]
	v_cndmask_b32_e64 v90, 0, 1.0, s[52:53]
	s_and_b64 s[52:53], s[50:51], s[18:19]
	v_cndmask_b32_e64 v91, 0, 1.0, s[52:53]
	s_and_b64 s[52:53], s[50:51], s[20:21]
	v_cndmask_b32_e64 v92, 0, 1.0, s[52:53]
	s_and_b64 s[52:53], s[50:51], s[22:23]
	v_cndmask_b32_e64 v93, 0, 1.0, s[52:53]
	s_and_b64 s[52:53], s[50:51], s[24:25]
	s_waitcnt vmcnt(4)
	v_cndmask_b32_e64 v94, 0, 1.0, s[52:53]
	s_and_b64 s[52:53], s[50:51], s[26:27]
	v_cndmask_b32_e64 v95, 0, 1.0, s[52:53]
	s_and_b64 s[52:53], s[50:51], s[28:29]
	s_and_b64 s[50:51], s[50:51], s[30:31]
	s_cmp_eq_u32 s49, 2
	v_cndmask_b32_e64 v97, 0, 1.0, s[50:51]
	s_cselect_b64 s[50:51], -1, 0
	s_and_b64 s[50:51], s[40:41], s[50:51]
	v_cndmask_b32_e64 v96, 0, 1.0, s[52:53]
	s_and_b64 s[52:53], s[50:51], vcc
	v_cndmask_b32_e64 v98, 0, 1.0, s[52:53]
	s_and_b64 s[52:53], s[50:51], s[2:3]
	v_cndmask_b32_e64 v99, 0, 1.0, s[52:53]
	s_and_b64 s[52:53], s[50:51], s[4:5]
	v_cndmask_b32_e64 v100, 0, 1.0, s[52:53]
	s_and_b64 s[52:53], s[50:51], s[6:7]
	v_cndmask_b32_e64 v101, 0, 1.0, s[52:53]
	s_and_b64 s[52:53], s[50:51], s[8:9]
	v_cndmask_b32_e64 v102, 0, 1.0, s[52:53]
	s_and_b64 s[52:53], s[50:51], s[10:11]
	v_cndmask_b32_e64 v103, 0, 1.0, s[52:53]
	s_and_b64 s[52:53], s[50:51], s[12:13]
	v_cndmask_b32_e64 v104, 0, 1.0, s[52:53]
	s_and_b64 s[52:53], s[50:51], s[14:15]
	v_cndmask_b32_e64 v105, 0, 1.0, s[52:53]
	s_and_b64 s[52:53], s[50:51], s[16:17]
	v_cndmask_b32_e64 v106, 0, 1.0, s[52:53]
	s_and_b64 s[52:53], s[50:51], s[18:19]
	v_cndmask_b32_e64 v107, 0, 1.0, s[52:53]
	s_and_b64 s[52:53], s[50:51], s[20:21]
	v_cndmask_b32_e64 v108, 0, 1.0, s[52:53]
	s_and_b64 s[52:53], s[50:51], s[22:23]
	v_cndmask_b32_e64 v109, 0, 1.0, s[52:53]
	s_and_b64 s[52:53], s[50:51], s[24:25]
	v_cndmask_b32_e64 v110, 0, 1.0, s[52:53]
	s_and_b64 s[52:53], s[50:51], s[26:27]
	v_cndmask_b32_e64 v111, 0, 1.0, s[52:53]
	s_and_b64 s[52:53], s[50:51], s[28:29]
	s_and_b64 s[50:51], s[50:51], s[30:31]
	s_cmp_eq_u32 s49, 3
	v_cndmask_b32_e64 v113, 0, 1.0, s[50:51]
	s_cselect_b64 s[50:51], -1, 0
	s_and_b64 s[50:51], s[40:41], s[50:51]
	s_and_b64 s[2:3], s[50:51], s[2:3]
	v_cndmask_b32_e64 v115, 0, 1.0, s[2:3]
	s_and_b64 s[2:3], s[50:51], s[4:5]
	v_cndmask_b32_e64 v116, 0, 1.0, s[2:3]
	s_and_b64 s[2:3], s[50:51], s[6:7]
	v_cndmask_b32_e64 v117, 0, 1.0, s[2:3]
	s_and_b64 s[2:3], s[50:51], s[8:9]
	v_cndmask_b32_e64 v118, 0, 1.0, s[2:3]
	s_and_b64 s[2:3], s[50:51], s[10:11]
	v_cndmask_b32_e64 v119, 0, 1.0, s[2:3]
	s_and_b64 s[2:3], s[50:51], s[12:13]
	v_cndmask_b32_e64 v120, 0, 1.0, s[2:3]
	s_and_b64 s[2:3], s[50:51], s[14:15]
	v_cndmask_b32_e64 v121, 0, 1.0, s[2:3]
	s_and_b64 s[2:3], s[50:51], s[16:17]
	s_waitcnt vmcnt(3)
	v_cndmask_b32_e64 v122, 0, 1.0, s[2:3]
	s_and_b64 s[2:3], s[50:51], s[18:19]
	v_cndmask_b32_e64 v123, 0, 1.0, s[2:3]
	s_and_b64 s[2:3], s[50:51], s[20:21]
	v_cndmask_b32_e64 v124, 0, 1.0, s[2:3]
	s_and_b64 s[2:3], s[50:51], s[22:23]
	v_cndmask_b32_e64 v125, 0, 1.0, s[2:3]
	s_and_b64 s[2:3], s[50:51], s[24:25]
	s_waitcnt vmcnt(2)
	v_cndmask_b32_e64 v126, 0, 1.0, s[2:3]
	s_and_b64 s[2:3], s[50:51], s[26:27]
	v_cndmask_b32_e64 v127, 0, 1.0, s[2:3]
	s_and_b64 s[2:3], s[50:51], s[28:29]
	v_cndmask_b32_e64 v112, 0, 1.0, s[52:53]
	s_and_b64 s[52:53], s[50:51], vcc
	v_cndmask_b32_e64 v128, 0, 1.0, s[2:3]
	s_and_b64 s[2:3], s[50:51], s[30:31]
	v_lshlrev_b32_e32 v180, 5, v183
	v_cndmask_b32_e64 v114, 0, 1.0, s[52:53]
	v_cndmask_b32_e64 v129, 0, 1.0, s[2:3]
	s_add_i32 s5, 0, 0x24000
	s_lshl_b32 s4, s49, 12

.LBB0_700:
	s_waitcnt vmcnt(0)
	v_cmp_eq_u32_e32 vcc, 0, v0
	s_xor_b64 s[0:1], s[0:1], -1
	s_mov_b64 s[86:87], -1
	s_mov_b64 s[2:3], vcc
	s_mov_b32 s101, s0
	s_waitcnt lgkmcnt(0)
	s_barrier
	s_and_saveexec_b64 s[0:1], s[2:3]
	s_cbranch_execz .LBB0_703
	s_mov_b64 s[2:3], exec
	v_mbcnt_lo_u32_b32 v2, s2, 0
	buffer_wbl2 sc1
	s_waitcnt vmcnt(0)
	s_waitcnt vmcnt(0)
	v_mbcnt_hi_u32_b32 v2, s3, v2
	v_cmp_eq_u32_e32 vcc, 0, v2
	s_and_b64 s[4:5], exec, vcc
	s_mov_b64 exec, s[4:5]
	s_cbranch_execz .LBB0_703
	s_lshl_b32 s4, s47, 6
	s_ashr_i32 s5, s4, 31
	s_lshl_b64 s[4:5], s[4:5], 2
	s_add_u32 s4, s82, s4
	s_addc_u32 s5, s83, s5
	s_bcnt1_i32_b64 s2, s[2:3]
	s_mov_b32 s100, 0x19400
	s_cmp_lg_u32 s101, 0
	s_cselect_b32 s100, 0x18000, s100
	v_mov_b32_e32 v2, s100
	v_mov_b32_e32 v3, s2
	global_atomic_add v2, v3, s[4:5]

.LBB0_740:
	s_waitcnt lgkmcnt(0)
	v_cmp_lt_i32_e32 vcc, v5, v6
	v_add_u32_e32 v13, v159, v130
	s_nop 0
	v_cndmask_b32_e32 v4, v4, v5, vcc
	v_lshlrev_b32_e32 v4, 2, v4
	ds_bpermute_b32 v4, v4, v7
	s_waitcnt lgkmcnt(0)
	v_add_f32_e32 v5, v7, v4
	v_div_scale_f32 v4, s[4:5], v5, v5, 1.0
	v_rcp_f32_e32 v6, v4
	v_log_f32_e32 v12, v5
	v_fma_f32 v7, -v4, v6, 1.0
	v_fmac_f32_e32 v6, v7, v6
	v_div_scale_f32 v7, vcc, 1.0, v5, 1.0
	v_mul_f32_e32 v8, v7, v6
	v_fma_f32 v9, -v4, v8, v7
	v_fmac_f32_e32 v8, v9, v6
	v_fma_f32 v4, -v4, v8, v7
	v_div_fmas_f32 v4, v4, v6, v8
	v_div_fixup_f32 v4, v4, v5, 1.0
	v_pk_mul_f32 v[6:7], v[82:83], v[4:5] op_sel_hi:[1,0]
	v_pk_mul_f32 v[8:9], v[84:85], v[4:5] op_sel_hi:[1,0]
	v_cvt_pk_bf16_f32 v6, v6, v7
	v_cvt_pk_bf16_f32 v7, v8, v9
	v_pk_mul_f32 v[8:9], v[86:87], v[4:5] op_sel_hi:[1,0]
	v_pk_mul_f32 v[10:11], v[88:89], v[4:5] op_sel_hi:[1,0]
	v_cvt_pk_bf16_f32 v8, v8, v9
	v_cvt_pk_bf16_f32 v9, v10, v11
	ds_write2_b64 v13, v[6:7], v[8:9] offset1:2
	v_pk_mul_f32 v[6:7], v[90:91], v[4:5] op_sel_hi:[1,0]
	v_pk_mul_f32 v[8:9], v[92:93], v[4:5] op_sel_hi:[1,0]
	v_cvt_pk_bf16_f32 v6, v6, v7
	v_cvt_pk_bf16_f32 v7, v8, v9
	v_pk_mul_f32 v[8:9], v[94:95], v[4:5] op_sel_hi:[1,0]
	v_pk_mul_f32 v[10:11], v[96:97], v[4:5] op_sel_hi:[1,0]
	v_cvt_pk_bf16_f32 v8, v8, v9
	v_cvt_pk_bf16_f32 v9, v10, v11
	ds_write2_b64 v13, v[6:7], v[8:9] offset0:4 offset1:6
	v_pk_mul_f32 v[6:7], v[66:67], v[4:5] op_sel_hi:[1,0]
	v_pk_mul_f32 v[8:9], v[68:69], v[4:5] op_sel_hi:[1,0]
	v_cvt_pk_bf16_f32 v6, v6, v7
	v_cvt_pk_bf16_f32 v7, v8, v9
	v_pk_mul_f32 v[8:9], v[70:71], v[4:5] op_sel_hi:[1,0]
	v_pk_mul_f32 v[10:11], v[72:73], v[4:5] op_sel_hi:[1,0]
	v_cvt_pk_bf16_f32 v8, v8, v9
	v_cvt_pk_bf16_f32 v9, v10, v11
	ds_write2_b64 v13, v[6:7], v[8:9] offset0:8 offset1:10
	v_pk_mul_f32 v[6:7], v[74:75], v[4:5] op_sel_hi:[1,0]
	v_pk_mul_f32 v[8:9], v[76:77], v[4:5] op_sel_hi:[1,0]
	v_cvt_pk_bf16_f32 v6, v6, v7
	v_cvt_pk_bf16_f32 v7, v8, v9
	v_pk_mul_f32 v[8:9], v[78:79], v[4:5] op_sel_hi:[1,0]
	v_pk_mul_f32 v[4:5], v[80:81], v[4:5] op_sel_hi:[1,0]
	v_cvt_pk_bf16_f32 v8, v8, v9
	v_cvt_pk_bf16_f32 v9, v4, v5
	v_add_f32_e32 v2, v2, v12
	ds_write2_b64 v13, v[6:7], v[8:9] offset0:12 offset1:14
	s_and_saveexec_b64 s[4:5], s[2:3]
	v_add_u32_e32 v4, s6, v137
	ds_write_b32 v4, v2 offset:4608
	s_or_b64 exec, exec, s[4:5]
	s_cmp_lg_u32 s98, 0
	s_cbranch_scc1 .Lsplit4_go3
	s_mov_b64 s[100:101], exec
	v_readlane_b32 s99, v254, 6
	s_nop 3
	s_mov_b32 exec_lo, s99
	s_mov_b32 exec_hi, 0
	s_cbranch_execz .Lsplit4_join3
	v_mov_b32_e32 v240, 0x7000
	v_mov_b32_e32 v242, 0

.Lsplit4_go3:
	s_lshl_b32 s4, s92, 2
	s_or_b32 s92, s4, s18
	v_or_b32_e32 v4, s24, v131
	s_lshl_b64 s[4:5], s[92:93], 12
	v_ashrrev_i32_e32 v5, 31, v4
	v_lshl_add_u64 v[4:5], s[4:5], 0, v[4:5]
	s_waitcnt lgkmcnt(0)
	v_lshlrev_b64 v[4:5], 7, v[4:5]
	v_add_u32_e32 v10, v158, v157
	v_lshl_add_u64 v[8:9], v[134:135], 0, v[4:5]
	ds_read_b128 v[4:7], v10
	s_waitcnt lgkmcnt(0)
	global_store_dwordx4 v[8:9], v[4:7], off sc1
	s_nop 1
	v_or_b32_e32 v4, s24, v156
	v_ashrrev_i32_e32 v5, 31, v4
	v_lshl_add_u64 v[4:5], s[4:5], 0, v[4:5]
	v_lshlrev_b64 v[4:5], 7, v[4:5]
	v_lshl_add_u64 v[8:9], v[134:135], 0, v[4:5]
	ds_read_b128 v[4:7], v10 offset:1152
	s_waitcnt lgkmcnt(0)
	global_store_dwordx4 v[8:9], v[4:7], off sc1
	s_nop 1
	v_or_b32_e32 v4, s24, v155
	v_ashrrev_i32_e32 v5, 31, v4
	v_lshl_add_u64 v[4:5], s[4:5], 0, v[4:5]
	v_lshlrev_b64 v[4:5], 7, v[4:5]
	v_lshl_add_u64 v[8:9], v[134:135], 0, v[4:5]
	ds_read_b128 v[4:7], v10 offset:2304
	s_waitcnt lgkmcnt(0)
	global_store_dwordx4 v[8:9], v[4:7], off sc1
	s_nop 1
	v_or_b32_e32 v4, s24, v154
	v_ashrrev_i32_e32 v5, 31, v4
	v_lshl_add_u64 v[4:5], s[4:5], 0, v[4:5]
	v_lshlrev_b64 v[4:5], 7, v[4:5]
	v_lshl_add_u64 v[8:9], v[134:135], 0, v[4:5]
	ds_read_b128 v[4:7], v10 offset:3456
	s_waitcnt lgkmcnt(0)
	global_store_dwordx4 v[8:9], v[4:7], off sc1
	s_nop 1
	s_and_saveexec_b64 s[70:71], s[2:3]
	s_cbranch_execz .LBB0_744
	s_lshl_b64 s[4:5], s[4:5], 2
	v_readlane_b32 s24, v254, 62
	s_add_u32 s4, s24, s4
	v_readlane_b32 s24, v254, 63
	s_addc_u32 s5, s24, s5
	v_ashrrev_i32_e32 v153, 31, v152
	v_lshl_add_u64 v[4:5], v[152:153], 2, s[4:5]
	global_store_dword v[4:5], v2, off sc1

.LBB0_779:
	s_waitcnt lgkmcnt(0)
	v_cmp_lt_i32_e32 vcc, v5, v6
	v_add_u32_e32 v13, v159, v130
	s_nop 0
	v_cndmask_b32_e32 v4, v4, v5, vcc
	v_lshlrev_b32_e32 v4, 2, v4
	ds_bpermute_b32 v4, v4, v7
	s_waitcnt lgkmcnt(0)
	v_add_f32_e32 v5, v7, v4
	v_div_scale_f32 v4, s[24:25], v5, v5, 1.0
	v_rcp_f32_e32 v6, v4
	v_log_f32_e32 v12, v5
	v_fma_f32 v7, -v4, v6, 1.0
	v_fmac_f32_e32 v6, v7, v6
	v_div_scale_f32 v7, vcc, 1.0, v5, 1.0
	v_mul_f32_e32 v8, v7, v6
	v_fma_f32 v9, -v4, v8, v7
	v_fmac_f32_e32 v8, v9, v6
	v_fma_f32 v4, -v4, v8, v7
	v_div_fmas_f32 v4, v4, v6, v8
	v_div_fixup_f32 v4, v4, v5, 1.0
	v_pk_mul_f32 v[6:7], v[82:83], v[4:5] op_sel_hi:[1,0]
	v_pk_mul_f32 v[8:9], v[84:85], v[4:5] op_sel_hi:[1,0]
	v_cvt_pk_bf16_f32 v6, v6, v7
	v_cvt_pk_bf16_f32 v7, v8, v9
	v_pk_mul_f32 v[8:9], v[86:87], v[4:5] op_sel_hi:[1,0]
	v_pk_mul_f32 v[10:11], v[88:89], v[4:5] op_sel_hi:[1,0]
	v_cvt_pk_bf16_f32 v8, v8, v9
	v_cvt_pk_bf16_f32 v9, v10, v11
	ds_write2_b64 v13, v[6:7], v[8:9] offset1:2
	v_pk_mul_f32 v[6:7], v[90:91], v[4:5] op_sel_hi:[1,0]
	v_pk_mul_f32 v[8:9], v[92:93], v[4:5] op_sel_hi:[1,0]
	v_cvt_pk_bf16_f32 v6, v6, v7
	v_cvt_pk_bf16_f32 v7, v8, v9
	v_pk_mul_f32 v[8:9], v[94:95], v[4:5] op_sel_hi:[1,0]
	v_pk_mul_f32 v[10:11], v[96:97], v[4:5] op_sel_hi:[1,0]
	v_cvt_pk_bf16_f32 v8, v8, v9
	v_cvt_pk_bf16_f32 v9, v10, v11
	ds_write2_b64 v13, v[6:7], v[8:9] offset0:4 offset1:6
	v_pk_mul_f32 v[6:7], v[66:67], v[4:5] op_sel_hi:[1,0]
	v_pk_mul_f32 v[8:9], v[68:69], v[4:5] op_sel_hi:[1,0]
	v_cvt_pk_bf16_f32 v6, v6, v7
	v_cvt_pk_bf16_f32 v7, v8, v9
	v_pk_mul_f32 v[8:9], v[70:71], v[4:5] op_sel_hi:[1,0]
	v_pk_mul_f32 v[10:11], v[72:73], v[4:5] op_sel_hi:[1,0]
	v_cvt_pk_bf16_f32 v8, v8, v9
	v_cvt_pk_bf16_f32 v9, v10, v11
	ds_write2_b64 v13, v[6:7], v[8:9] offset0:8 offset1:10
	v_pk_mul_f32 v[6:7], v[74:75], v[4:5] op_sel_hi:[1,0]
	v_pk_mul_f32 v[8:9], v[76:77], v[4:5] op_sel_hi:[1,0]
	v_cvt_pk_bf16_f32 v6, v6, v7
	v_cvt_pk_bf16_f32 v7, v8, v9
	v_pk_mul_f32 v[8:9], v[78:79], v[4:5] op_sel_hi:[1,0]
	v_pk_mul_f32 v[4:5], v[80:81], v[4:5] op_sel_hi:[1,0]
	v_cvt_pk_bf16_f32 v8, v8, v9
	v_cvt_pk_bf16_f32 v9, v4, v5
	v_add_f32_e32 v2, v2, v12
	ds_write2_b64 v13, v[6:7], v[8:9] offset0:12 offset1:14
	s_and_saveexec_b64 s[70:71], s[2:3]
	v_add_u32_e32 v4, s6, v137
	ds_write_b32 v4, v2 offset:4608
	s_or_b64 exec, exec, s[70:71]
	s_cmp_lg_u32 s98, 0
	s_cbranch_scc1 .Lsplit4_go4
	s_mov_b64 s[100:101], exec
	v_readlane_b32 s99, v254, 6
	s_nop 3
	s_mov_b32 exec_lo, s99
	s_mov_b32 exec_hi, 0
	s_cbranch_execz .Lsplit4_join4
	v_mov_b32_e32 v240, 0x7000
	v_mov_b32_e32 v242, 0

.Lsplit4_go4:
	s_lshl_b32 s4, s4, 4
	s_or_b32 s4, s4, s19
	s_ashr_i32 s5, s4, 31
	s_lshl_b64 s[4:5], s[4:5], 10
	v_lshl_add_u64 v[4:5], s[4:5], 0, v[138:139]
	s_waitcnt lgkmcnt(0)
	v_lshlrev_b64 v[4:5], 7, v[4:5]
	v_add_u32_e32 v10, v158, v157
	v_lshl_add_u64 v[8:9], v[132:133], 0, v[4:5]
	ds_read_b128 v[4:7], v10
	s_waitcnt lgkmcnt(0)
	global_store_dwordx4 v[8:9], v[4:7], off sc1
	s_nop 1
	v_lshl_add_u64 v[4:5], s[4:5], 0, v[140:141]
	v_lshlrev_b64 v[4:5], 7, v[4:5]
	v_lshl_add_u64 v[8:9], v[132:133], 0, v[4:5]
	ds_read_b128 v[4:7], v10 offset:1152
	s_waitcnt lgkmcnt(0)
	global_store_dwordx4 v[8:9], v[4:7], off sc1
	s_nop 1
	v_lshl_add_u64 v[4:5], s[4:5], 0, v[142:143]
	v_lshlrev_b64 v[4:5], 7, v[4:5]
	v_lshl_add_u64 v[8:9], v[132:133], 0, v[4:5]
	ds_read_b128 v[4:7], v10 offset:2304
	s_waitcnt lgkmcnt(0)
	global_store_dwordx4 v[8:9], v[4:7], off sc1
	s_nop 1
	v_lshl_add_u64 v[4:5], s[4:5], 0, v[144:145]
	v_lshlrev_b64 v[4:5], 7, v[4:5]
	v_lshl_add_u64 v[8:9], v[132:133], 0, v[4:5]
	ds_read_b128 v[4:7], v10 offset:3456
	s_waitcnt lgkmcnt(0)
	global_store_dwordx4 v[8:9], v[4:7], off sc1
	s_nop 1
	s_and_saveexec_b64 s[70:71], s[2:3]
	s_cbranch_execz .LBB0_704
	v_lshl_add_u64 v[4:5], s[4:5], 2, v[150:151]
	global_store_dword v[4:5], v2, off sc1
	s_branch .LBB0_704

.LBB0_874:
	s_or_b64 exec, exec, s[0:1]
	s_or_b32 s5, s48, s47
	s_or_b32 s0, s5, s4
	s_mul_hi_i32 s1, s0, 0x12000
	s_mul_i32 s0, s0, 0x12000
	s_add_u32 s0, s82, s0
	s_addc_u32 s1, s83, s1
	s_add_u32 s0, s0, 0xb000000
	s_addc_u32 s1, s1, 0
	s_and_b32 s2, s56, 0xffffff80
	v_lshlrev_b32_e32 v218, 4, v195
	s_cmpk_lg_i32 s2, 0x100
	s_mov_b64 s[2:3], -1
	s_cbranch_scc0 .LBB0_895
	s_lshl_b32 s2, s10, 4
	s_or_b32 s8, s2, s49
	s_ashr_i32 s9, s8, 31
	s_lshl_b64 s[2:3], s[8:9], 16
	s_add_u32 s2, s82, s2
	s_addc_u32 s3, s83, s3
	s_add_u32 s6, s2, 0x100000
	s_addc_u32 s7, s3, 0
	s_cmp_gt_i32 s33, 3
	s_mov_b64 s[2:3], -1
	s_cbranch_scc0 .LBB0_888
	v_and_b32_e32 v26, 7, v194
	v_lshlrev_b32_e32 v18, 6, v26
	global_load_dwordx4 v[2:5], v18, s[72:73] offset:48
	global_load_dwordx4 v[6:9], v18, s[72:73] offset:32
	global_load_dwordx4 v[10:13], v18, s[72:73] offset:16
	global_load_dwordx4 v[14:17], v18, s[72:73]
	s_add_i32 s12, s33, -6
	v_lshlrev_b32_e32 v18, 4, v26
	s_waitcnt vmcnt(12)
	v_mov_b32_e32 v83, 0
	s_cmp_eq_u32 s46, 0
	s_mov_b32 s11, 0
	s_cbranch_scc1 .LBB0_878
	v_mov_b32_e32 v219, v83
	s_lshl_b32 s2, s12, 10
	v_lshl_add_u64 v[20:21], s[6:7], 0, v[218:219]
	s_mov_b64 s[14:15], 0x8000
	v_lshl_add_u64 v[24:25], v[20:21], 0, s[14:15]
	s_add_i32 s14, s2, 0x800
	s_ashr_i32 s15, s14, 31
	v_lshl_add_u64 v[34:35], v[24:25], 0, s[14:15]
	s_add_i32 s14, s2, 0x1000
	s_ashr_i32 s15, s14, 31
	v_lshl_add_u64 v[40:41], v[24:25], 0, s[14:15]
	s_add_i32 s14, s2, 0x1800
	s_ashr_i32 s15, s14, 31
	v_lshl_add_u64 v[42:43], v[24:25], 0, s[14:15]
	s_add_i32 s14, s2, 0x2000
	s_ashr_i32 s15, s14, 31
	v_lshl_add_u64 v[48:49], v[24:25], 0, s[14:15]
	s_add_i32 s14, s2, 0x2800
	s_ashr_i32 s15, s14, 31
	v_lshl_add_u64 v[50:51], v[24:25], 0, s[14:15]
	s_add_i32 s14, s2, 0x3000
	s_ashr_i32 s15, s14, 31
	v_lshl_add_u64 v[56:57], v[24:25], 0, s[14:15]
	s_add_i32 s14, s2, 0x3800
	s_ashr_i32 s15, s14, 31
	v_lshl_add_u64 v[58:59], v[24:25], 0, s[14:15]
	s_add_i32 s14, s2, 0x4000
	s_ashr_i32 s15, s14, 31
	v_lshl_add_u64 v[64:65], v[24:25], 0, s[14:15]
	s_add_i32 s14, s2, 0x4800
	s_ashr_i32 s15, s14, 31
	v_lshl_add_u64 v[66:67], v[24:25], 0, s[14:15]
	s_add_i32 s14, s2, 0x5000
	s_ashr_i32 s15, s14, 31
	v_lshl_add_u64 v[72:73], v[24:25], 0, s[14:15]
	s_add_i32 s14, s2, 0x5800
	s_ashr_i32 s15, s14, 31
	v_lshl_add_u64 v[74:75], v[24:25], 0, s[14:15]
	s_add_i32 s14, s2, 0x6000
	s_ashr_i32 s15, s14, 31
	v_lshl_add_u64 v[80:81], v[24:25], 0, s[14:15]
	s_add_i32 s14, s2, 0x6800
	s_ashr_i32 s15, s14, 31
	s_ashr_i32 s3, s2, 31
	v_lshl_add_u64 v[84:85], v[24:25], 0, s[14:15]
	s_add_i32 s14, s2, 0x7000
	v_lshl_add_u64 v[32:33], v[24:25], 0, s[2:3]
	s_ashr_i32 s15, s14, 31
	global_load_dwordx4 v[20:23], v[32:33], off
	global_load_dwordx4 v[28:31], v[34:35], off
	s_nop 0
	global_load_dwordx4 v[32:35], v[40:41], off
	global_load_dwordx4 v[36:39], v[42:43], off
	s_nop 0
	global_load_dwordx4 v[40:43], v[48:49], off
	global_load_dwordx4 v[44:47], v[50:51], off
	s_nop 0
	global_load_dwordx4 v[48:51], v[56:57], off
	global_load_dwordx4 v[52:55], v[58:59], off
	s_nop 0
	global_load_dwordx4 v[56:59], v[64:65], off
	global_load_dwordx4 v[60:63], v[66:67], off
	s_nop 0
	global_load_dwordx4 v[64:67], v[72:73], off
	global_load_dwordx4 v[68:71], v[74:75], off
	s_nop 0
	global_load_dwordx4 v[72:75], v[80:81], off
	global_load_dwordx4 v[76:79], v[84:85], off
	v_lshl_add_u64 v[80:81], v[24:25], 0, s[14:15]
	s_add_i32 s14, s2, 0x7800
	s_ashr_i32 s15, s14, 31
	v_lshl_add_u64 v[24:25], v[24:25], 0, s[14:15]
	global_load_dwordx4 v[84:87], v[80:81], off
	global_load_dwordx4 v[88:91], v[24:25], off
	s_add_i32 s2, s2, 0
	v_add_u32_e32 v19, s2, v218
	v_add_u32_e32 v24, 0xe000, v19
	s_waitcnt vmcnt(15)
	ds_write_b128 v19, v[20:23] offset:57344
	s_waitcnt vmcnt(14)
	ds_write_b128 v19, v[28:31] offset:59392
	s_waitcnt vmcnt(13)
	ds_write_b128 v19, v[32:35] offset:61440
	s_waitcnt vmcnt(12)
	ds_write_b128 v19, v[36:39] offset:63488
	s_waitcnt vmcnt(11)
	ds_write_b128 v24, v[40:43] offset:8192
	s_waitcnt vmcnt(10)
	ds_write_b128 v24, v[44:47] offset:10240
	s_waitcnt vmcnt(9)
	ds_write_b128 v24, v[48:51] offset:12288
	s_waitcnt vmcnt(8)
	ds_write_b128 v24, v[52:55] offset:14336
	s_waitcnt vmcnt(7)
	ds_write_b128 v24, v[56:59] offset:16384
	s_waitcnt vmcnt(6)
	ds_write_b128 v24, v[60:63] offset:18432
	s_waitcnt vmcnt(5)
	ds_write_b128 v24, v[64:67] offset:20480
	s_waitcnt vmcnt(4)
	ds_write_b128 v24, v[68:71] offset:22528
	s_waitcnt vmcnt(3)
	ds_write_b128 v24, v[72:75] offset:24576
	s_waitcnt vmcnt(2)
	ds_write_b128 v24, v[76:79] offset:26624
	s_waitcnt vmcnt(1)
	ds_write_b128 v24, v[84:87] offset:28672
	s_waitcnt vmcnt(0)
	ds_write_b128 v24, v[88:91] offset:30720
	s_waitcnt lgkmcnt(0)
	s_barrier
